# next-quarter k/v prefetch issued at the top of a quarter (before the staging) and next unit's tiles loaded straight into the prefetch registers
# speedup vs baseline: 1.0012x; 1.0012x over previous
.LBB0_959:
	s_cmpk_eq_i32 s52, 0x180
	s_mov_b64 s[12:13], -1
	s_cbranch_scc1 .Lr1h_last
	v_lshl_add_u64 v[0:1], v[228:229], 0, s[0:1]
	v_lshl_add_u64 v[4:5], v[226:227], 0, s[0:1]
	v_lshl_add_u64 v[8:9], v[224:225], 0, s[0:1]
	v_lshl_add_u64 v[12:13], v[222:223], 0, s[0:1]
	v_lshl_add_u64 v[16:17], v[220:221], 0, s[0:1]
	v_lshl_add_u64 v[20:21], v[218:219], 0, s[0:1]
	v_lshl_add_u64 v[24:25], v[216:217], 0, s[0:1]
	v_lshl_add_u64 v[28:29], v[214:215], 0, s[0:1]
	v_lshl_add_u64 v[32:33], v[212:213], 0, s[0:1]
	v_lshl_add_u64 v[36:37], v[210:211], 0, s[0:1]
	global_load_dwordx4 v[0:3], v[0:1], off
	global_load_dwordx4 v[4:7], v[4:5], off
	global_load_dwordx4 v[8:11], v[8:9], off
	global_load_dwordx4 v[12:15], v[12:13], off
	global_load_dwordx4 v[16:19], v[16:17], off
	global_load_dwordx4 v[20:23], v[20:21], off
	global_load_dwordx4 v[24:27], v[24:25], off
	global_load_dwordx4 v[28:31], v[28:29], off
	global_load_dwordx4 v[32:35], v[32:33], off
	global_load_dwordx4 v[36:39], v[36:37], off
	s_branch .Lr1h_done
.Lr1h_last:
	s_andn2_b64 vcc, exec, s[10:11]
	s_cbranch_vccnz .Lr1h_done
	global_load_dwordx4 v[0:3], v[190:191], off
	global_load_dwordx4 v[4:7], v[192:193], off
	global_load_dwordx4 v[8:11], v[194:195], off
	global_load_dwordx4 v[12:15], v[196:197], off
	global_load_dwordx4 v[16:19], v[198:199], off
	global_load_dwordx4 v[20:23], v[200:201], off
	global_load_dwordx4 v[24:27], v[202:203], off
	global_load_dwordx4 v[28:31], v[204:205], off
	global_load_dwordx4 v[32:35], v[206:207], off
	global_load_dwordx4 v[36:39], v[208:209], off
.Lr1h_done:
	s_barrier
	ds_write_b128 v238, v[104:107]
	ds_write_b128 v239, v[108:111]
	ds_write_b128 v240, v[112:115]
	ds_write_b128 v241, v[116:119]
	ds_write_b128 v242, v[120:123]
	ds_write_b128 v243, v[124:127]
	ds_write_b128 v244, v[128:131]
	ds_write_b128 v245, v[132:135]
	v_lshrrev_b32_e32 v104, 3, v230
	v_add_u32_e32 v105, s52, v104
	v_add_u32_e32 v106, 64, v105
	v_sub_u32_e32 v107, 0x1ff, v105
	v_sub_u32_e32 v108, 0x1ff, v106
	v_cvt_f32_u32_e32 v105, v105
	v_cvt_f32_u32_e32 v106, v106
	v_cvt_f32_u32_e32 v107, v107
	v_cvt_f32_u32_e32 v108, v108
	v_mul_f32_e32 v105, v254, v105
	v_mul_f32_e32 v106, v254, v106
	v_mul_f32_e32 v107, v253, v107
	v_mul_f32_e32 v108, v253, v108
	v_exp_f32_e32 v105, v105
	v_exp_f32_e32 v106, v106
	v_exp_f32_e32 v107, v107
	v_exp_f32_e32 v108, v108
	v_lshlrev_b32_e32 v112, 16, v136
	v_and_b32_e32 v113, 0xffff0000, v136
	v_lshlrev_b32_e32 v114, 16, v137
	v_and_b32_e32 v115, 0xffff0000, v137
	v_lshlrev_b32_e32 v116, 16, v138
	v_and_b32_e32 v117, 0xffff0000, v138
	v_lshlrev_b32_e32 v118, 16, v139
	v_and_b32_e32 v119, 0xffff0000, v139
	v_mul_f32_e32 v109, v107, v112
	v_mul_f32_e32 v110, v107, v113
	v_cvt_pk_bf16_f32 v128, v109, v110
	v_mul_f32_e32 v109, v107, v114
	v_mul_f32_e32 v110, v107, v115
	v_cvt_pk_bf16_f32 v129, v109, v110
	v_mul_f32_e32 v109, v107, v116
	v_mul_f32_e32 v110, v107, v117
	v_cvt_pk_bf16_f32 v130, v109, v110
	v_mul_f32_e32 v109, v107, v118
	v_mul_f32_e32 v110, v107, v119
	v_cvt_pk_bf16_f32 v131, v109, v110
	ds_write_b128 v246, v[128:131]
	v_mul_f32_e32 v109, v105, v112
	v_mul_f32_e32 v110, v105, v113
	v_cvt_pk_bf16_f32 v132, v109, v110
	v_mul_f32_e32 v109, v105, v114
	v_mul_f32_e32 v110, v105, v115
	v_cvt_pk_bf16_f32 v133, v109, v110
	v_mul_f32_e32 v109, v105, v116
	v_mul_f32_e32 v110, v105, v117
	v_cvt_pk_bf16_f32 v134, v109, v110
	v_mul_f32_e32 v109, v105, v118
	v_mul_f32_e32 v110, v105, v119
	v_cvt_pk_bf16_f32 v135, v109, v110
	ds_write_b128 v246, v[132:135] offset:20480
	v_lshlrev_b32_e32 v120, 16, v140
	v_and_b32_e32 v121, 0xffff0000, v140
	v_lshlrev_b32_e32 v122, 16, v141
	v_and_b32_e32 v123, 0xffff0000, v141
	v_lshlrev_b32_e32 v124, 16, v142
	v_and_b32_e32 v125, 0xffff0000, v142
	v_lshlrev_b32_e32 v126, 16, v143
	v_and_b32_e32 v127, 0xffff0000, v143
	v_mul_f32_e32 v109, v108, v120
	v_mul_f32_e32 v110, v108, v121
	v_cvt_pk_bf16_f32 v128, v109, v110
	v_mul_f32_e32 v109, v108, v122
	v_mul_f32_e32 v110, v108, v123
	v_cvt_pk_bf16_f32 v129, v109, v110
	v_mul_f32_e32 v109, v108, v124
	v_mul_f32_e32 v110, v108, v125
	v_cvt_pk_bf16_f32 v130, v109, v110
	v_mul_f32_e32 v109, v108, v126
	v_mul_f32_e32 v110, v108, v127
	v_cvt_pk_bf16_f32 v131, v109, v110
	ds_write_b128 v247, v[128:131]
	v_mul_f32_e32 v109, v106, v120
	v_mul_f32_e32 v110, v106, v121
	v_cvt_pk_bf16_f32 v132, v109, v110
	v_mul_f32_e32 v109, v106, v122
	v_mul_f32_e32 v110, v106, v123
	v_cvt_pk_bf16_f32 v133, v109, v110
	v_mul_f32_e32 v109, v106, v124
	v_mul_f32_e32 v110, v106, v125
	v_cvt_pk_bf16_f32 v134, v109, v110
	v_mul_f32_e32 v109, v106, v126
	v_mul_f32_e32 v110, v106, v127
	v_cvt_pk_bf16_f32 v135, v109, v110
	ds_write_b128 v247, v[132:135] offset:20480
	s_waitcnt lgkmcnt(0)
	s_barrier
